# attention FIXM loop: VALU re-spaced around MFMAs (two 6-exp gaps split across the next MFMA; the 20-VALU run before the mid barrier moved behind its MFMA)
# baseline (speedup 1.0000x reference)
.LBB0_898:
	s_add_i32 s9, s3, -1
	s_min_u32 s9, s9, s2
	s_lshl_b32 s9, s9, 6
	s_waitcnt vmcnt(1)
	ds_write_b128 v142, v[112:115] offset:16384
	s_waitcnt vmcnt(0)
	ds_write_b128 v142, v[116:119] offset:24576
	v_mad_u64_u32 v[64:65], s[18:19], s9, v237, v[132:133]
	global_load_dwordx4 v[120:123], v[64:65], off offset:2048
	global_load_dwordx4 v[124:127], v[136:137], off offset:-128
	ds_read_b128 v[64:67], v144 offset:8192
	ds_read_b128 v[68:71], v144 offset:12288
	ds_read_b128 v[72:75], v141 offset:8192
	ds_read_b128 v[76:79], v141 offset:12288
	v_exp_f32_e32 v151, v48
	v_exp_f32_e32 v152, v49
	s_waitcnt lgkmcnt(3)
	v_mfma_f32_32x32x16_bf16 v[16:31], v[64:67], v[80:83], v[16:31]
	v_exp_f32_e32 v153, v50
	v_exp_f32_e32 v154, v51
	ds_read_b128 v[48:51], v140 offset:8192
	ds_read_b128 v[64:67], v140 offset:12288
	v_exp_f32_e32 v155, v52
	s_waitcnt lgkmcnt(4)
	v_mfma_f32_32x32x16_bf16 v[0:15], v[68:71], v[80:83], v[0:15]
	v_exp_f32_e32 v156, v53
	v_exp_f32_e32 v159, v54
	v_exp_f32_e32 v160, v55
	v_exp_f32_e32 v162, v57
	s_waitcnt lgkmcnt(3)
	v_mfma_f32_32x32x16_bf16 v[16:31], v[72:75], v[84:87], v[16:31]
	ds_read_b128 v[68:71], v139 offset:8192
	ds_read_b128 v[80:83], v139 offset:12288
	v_add_f32_e32 v157, v155, v151
	v_add_f32_e32 v158, v156, v152
	ds_read_b128 v[52:55], v164
	ds_read_b128 v[72:75], v164 offset:4096
	v_add_f32_e32 v161, v159, v153
	s_waitcnt lgkmcnt(6)
	v_mfma_f32_32x32x16_bf16 v[0:15], v[76:79], v[84:87], v[0:15]
	v_exp_f32_e32 v77, v56
	v_add_f32_e32 v76, v160, v154
	v_exp_f32_e32 v62, v62
	ds_read_b128 v[112:115], v165
	ds_read_b128 v[116:119], v165 offset:4096
	v_cvt_pk_bf16_f32 v56, v151, v152
	s_waitcnt lgkmcnt(7)
	v_mfma_f32_32x32x16_bf16 v[16:31], v[48:51], v[88:91], v[16:31]
	v_exp_f32_e32 v49, v58
	v_exp_f32_e32 v50, v59
	v_add_f32_e32 v48, v77, v157
	v_add_f32_e32 v51, v162, v158
	v_add_f32_e32 v78, v49, v161
	v_add_f32_e32 v76, v50, v76
	s_waitcnt lgkmcnt(6)
	v_mfma_f32_32x32x16_bf16 v[0:15], v[64:67], v[88:91], v[0:15]
	v_exp_f32_e32 v60, v60
	v_add_f32_e32 v151, v62, v78
	v_exp_f32_e32 v61, v61
	v_exp_f32_e32 v63, v63
	v_cvt_pk_bf16_f32 v59, v159, v160
	v_exp_f32_e32 v160, v33
	s_waitcnt lgkmcnt(5)
	v_mfma_f32_32x32x16_bf16 v[16:31], v[68:71], v[92:95], v[16:31]
	v_cvt_pk_bf16_f32 v57, v153, v154
	v_cvt_pk_bf16_f32 v58, v155, v156
	v_add_f32_e32 v48, v60, v48
	v_add_f32_e32 v51, v61, v51
	v_cvt_pk_bf16_f32 v49, v49, v50
	s_waitcnt lgkmcnt(4)
	v_mfma_f32_32x32x16_bf16 v[0:15], v[80:83], v[92:95], v[0:15]
	v_exp_f32_e32 v95, v32
	v_add_f32_e32 v32, v63, v76
	v_add_f32_e32 v163, v160, v51
	v_add_f32_e32 v161, v95, v48
	v_cvt_pk_bf16_f32 v48, v77, v162
	v_cvt_pk_bf16_f32 v51, v62, v63
	s_waitcnt lgkmcnt(3)
	v_mfma_f32_32x32x16_bf16 v[78:93], v[52:55], v[96:99], 0
	v_cvt_pk_bf16_f32 v50, v60, v61
	v_exp_f32_e32 v60, v34
	v_exp_f32_e32 v61, v35
	v_exp_f32_e32 v36, v36
	v_exp_f32_e32 v37, v37
	s_waitcnt lgkmcnt(2)
	v_mfma_f32_32x32x16_bf16 v[62:77], v[72:75], v[96:99], 0
	v_exp_f32_e32 v38, v38
	v_exp_f32_e32 v39, v39
	ds_read_b128 v[52:55], v166
	ds_read_b128 v[152:155], v166 offset:4096
	v_add_f32_e32 v151, v60, v151
	v_add_f32_e32 v162, v61, v32
	s_waitcnt lgkmcnt(3)
	v_mfma_f32_32x32x16_bf16 v[78:93], v[112:115], v[100:103], v[78:93]
	v_add_f32_e32 v112, v36, v161
	v_add_f32_e32 v113, v37, v163
	v_add_f32_e32 v114, v38, v151
	v_exp_f32_e32 v115, v40
	v_add_f32_e32 v40, v39, v162
	ds_read_b128 v[32:35], v167
	ds_read_b128 v[156:159], v167 offset:4096
	s_waitcnt lgkmcnt(4)
	v_mfma_f32_32x32x16_bf16 v[62:77], v[116:119], v[100:103], v[62:77]
	v_exp_f32_e32 v116, v41
	v_add_f32_e32 v41, v115, v112
	s_min_u32 s9, s3, s2
	s_lshl_b32 s9, s9, 6
	v_add_f32_e32 v112, v116, v113
	s_waitcnt lgkmcnt(3)
	v_mfma_f32_32x32x16_bf16 v[78:93], v[52:55], v[104:107], v[78:93]
	v_cvt_pk_bf16_f32 v54, v36, v37
	v_cvt_pk_bf16_f32 v55, v38, v39
	s_waitcnt lgkmcnt(1)
	v_mfma_f32_32x32x16_bf16 v[78:93], v[32:35], v[108:111], v[78:93]
	v_exp_f32_e32 v37, v42
	v_exp_f32_e32 v38, v43
	v_exp_f32_e32 v39, v44
	v_exp_f32_e32 v44, v45
	v_exp_f32_e32 v45, v46
	v_exp_f32_e32 v46, v47
	v_cvt_pk_bf16_f32 v52, v95, v160
	v_cvt_pk_bf16_f32 v53, v60, v61
	v_add_f32_e32 v36, v37, v114
	v_add_f32_e32 v43, v38, v40
	v_add_f32_e32 v40, v39, v41
	v_add_f32_e32 v42, v44, v112
	v_add_f32_e32 v41, v45, v36
	v_add_f32_e32 v43, v46, v43
	v_cvt_pk_bf16_f32 v36, v115, v116
	v_cvt_pk_bf16_f32 v37, v37, v38
	v_cvt_pk_bf16_f32 v38, v39, v44
	v_cvt_pk_bf16_f32 v39, v45, v46
	s_waitcnt lgkmcnt(0)
	s_barrier
	v_mad_u64_u32 v[32:33], s[18:19], s9, v237, v[132:133]
	global_load_dwordx4 v[112:115], v[32:33], off offset:2048
	global_load_dwordx4 v[116:119], v[136:137], off
	v_add_f32_e64 v32, v40, v42
	v_add_f32_e64 v33, v41, v43
	s_waitcnt vmcnt(3)
	ds_write_b128 v142, v[120:123]
	s_waitcnt vmcnt(2)
	ds_write_b128 v142, v[124:127] offset:8192
	v_mfma_f32_32x32x16_bf16 v[62:77], v[152:155], v[104:107], v[62:77]
	v_add_f32_e32 v32, v32, v33
	v_add_f32_e32 v150, v150, v32
	s_waitcnt lgkmcnt(2)
	v_mfma_f32_32x32x16_bf16 v[62:77], v[156:159], v[108:111], v[62:77]
	ds_read_b128 v[32:35], v144 offset:24576
	ds_read_b128 v[40:43], v144 offset:28672
	ds_read_b128 v[44:47], v141 offset:24576
	ds_read_b128 v[120:123], v141 offset:28672
	v_exp_f32_e32 v60, v78
	s_waitcnt lgkmcnt(3)
	v_mfma_f32_32x32x16_bf16 v[16:31], v[32:35], v[56:59], v[16:31]
	v_exp_f32_e32 v61, v79
	v_exp_f32_e32 v95, v80
	v_exp_f32_e32 v81, v81
	ds_read_b128 v[152:155], v140 offset:24576
	ds_read_b128 v[156:159], v140 offset:28672
	s_waitcnt lgkmcnt(4)
	v_mfma_f32_32x32x16_bf16 v[0:15], v[40:43], v[56:59], v[0:15]
	v_exp_f32_e32 v82, v82
	v_exp_f32_e32 v83, v83
	v_add_f32_e32 v78, v82, v60
	v_add_f32_e32 v79, v83, v61
	s_waitcnt lgkmcnt(2)
	v_mfma_f32_32x32x16_bf16 v[0:15], v[120:123], v[48:51], v[0:15]
	ds_read_b128 v[56:59], v139 offset:24576
	ds_read_b128 v[160:163], v139 offset:28672
	ds_read_b128 v[40:43], v164 offset:16384
	ds_read_b128 v[32:35], v164 offset:20480
	v_cvt_pk_bf16_f32 v82, v82, v83
	v_exp_f32_e32 v151, v62
	v_exp_f32_e32 v64, v64
	v_exp_f32_e32 v65, v65
	v_mfma_f32_32x32x16_bf16 v[16:31], v[44:47], v[48:51], v[16:31]
	v_exp_f32_e32 v44, v84
	v_exp_f32_e32 v45, v85
	v_exp_f32_e32 v84, v86
	v_exp_f32_e32 v85, v87
	v_add_f32_e32 v46, v44, v95
	v_add_f32_e32 v47, v45, v81
	v_add_f32_e32 v48, v84, v78
	s_waitcnt lgkmcnt(4)
	v_mfma_f32_32x32x16_bf16 v[0:15], v[156:159], v[52:55], v[0:15]
	v_add_f32_e32 v49, v85, v79
	v_exp_f32_e32 v78, v88
	v_exp_f32_e32 v79, v89
	v_exp_f32_e32 v87, v92
	v_cvt_pk_bf16_f32 v83, v44, v45
	v_exp_f32_e32 v44, v90
	v_mfma_f32_32x32x16_bf16 v[16:31], v[152:155], v[52:55], v[16:31]
	v_exp_f32_e32 v45, v91
	v_exp_f32_e32 v92, v93
	v_add_f32_e32 v46, v78, v46
	v_add_f32_e32 v47, v79, v47
	ds_read_b128 v[124:127], v165 offset:16384
	ds_read_b128 v[120:123], v165 offset:20480
	s_waitcnt lgkmcnt(4)
	v_mfma_f32_32x32x16_bf16 v[0:15], v[160:163], v[36:39], v[0:15]
	v_exp_f32_e32 v160, v63
	v_cvt_pk_bf16_f32 v80, v60, v61
	v_cvt_pk_bf16_f32 v81, v95, v81
	v_add_f32_e32 v48, v44, v48
	v_add_f32_e32 v49, v45, v49
	v_add_f32_e32 v46, v87, v46
	v_add_f32_e32 v47, v92, v47
	v_mfma_f32_32x32x16_bf16 v[16:31], v[56:59], v[36:39], v[16:31]
	v_add_f32_e32 v161, v151, v48
	v_add_f32_e32 v162, v160, v49
	v_cvt_pk_bf16_f32 v84, v84, v85
	v_cvt_pk_bf16_f32 v85, v78, v79
	v_cvt_pk_bf16_f32 v86, v44, v45
	v_add_f32_e32 v78, v64, v46
	v_add_f32_e32 v79, v65, v47
	s_waitcnt lgkmcnt(3)
	v_mfma_f32_32x32x16_bf16 v[48:63], v[40:43], v[96:99], 0
	ds_read_b128 v[88:91], v166 offset:16384
	ds_read_b128 v[152:155], v166 offset:20480
	v_exp_f32_e32 v66, v66
	v_exp_f32_e32 v67, v67
	v_exp_f32_e32 v68, v68
	v_exp_f32_e32 v69, v69
	v_cvt_pk_bf16_f32 v87, v87, v92
	s_waitcnt lgkmcnt(4)
	v_mfma_f32_32x32x16_bf16 v[32:47], v[32:35], v[96:99], 0
	ds_read_b128 v[156:159], v167 offset:16384
	ds_read_b128 v[92:95], v167 offset:20480
	v_add_f32_e32 v161, v66, v161
	v_add_f32_e32 v162, v67, v162
	v_add_f32_e32 v78, v68, v78
	v_add_f32_e32 v79, v69, v79
	s_waitcnt lgkmcnt(5)
	v_mfma_f32_32x32x16_bf16 v[48:63], v[124:127], v[100:103], v[48:63]
	v_exp_f32_e32 v70, v70
	v_exp_f32_e32 v71, v71
	s_add_i32 s9, s3, 2
	s_add_i32 s3, s3, -2
	v_lshl_add_u64 v[136:137], v[136:137], 0, s[22:23]
	s_waitcnt lgkmcnt(4)
	v_mfma_f32_32x32x16_bf16 v[32:47], v[120:123], v[100:103], v[32:47]
	v_add_f32_e32 v120, v70, v161
	v_add_f32_e32 v121, v71, v162
	s_cmp_lt_u32 s3, s2
	s_mov_b32 s3, s9
	s_waitcnt lgkmcnt(3)
	v_mfma_f32_32x32x16_bf16 v[48:63], v[88:91], v[104:107], v[48:63]
	v_cvt_pk_bf16_f32 v91, v68, v69
	v_exp_f32_e32 v68, v72
	v_exp_f32_e32 v69, v73
	v_exp_f32_e32 v72, v74
	v_exp_f32_e32 v73, v75
	s_waitcnt lgkmcnt(2)
	v_mfma_f32_32x32x16_bf16 v[32:47], v[152:155], v[104:107], v[32:47]
	v_exp_f32_e32 v74, v76
	v_exp_f32_e32 v75, v77
	v_cvt_pk_bf16_f32 v88, v151, v160
	v_cvt_pk_bf16_f32 v89, v64, v65
	v_cvt_pk_bf16_f32 v90, v66, v67
	v_add_f32_e32 v65, v68, v78
	v_add_f32_e32 v67, v69, v79
	s_waitcnt lgkmcnt(1)
	v_mfma_f32_32x32x16_bf16 v[48:63], v[156:159], v[108:111], v[48:63]
	v_add_f32_e32 v64, v72, v120
	v_add_f32_e32 v66, v73, v121
	v_add_f32_e32 v65, v74, v65
	v_add_f32_e32 v67, v75, v67
	s_waitcnt lgkmcnt(0)
	v_mfma_f32_32x32x16_bf16 v[32:47], v[92:95], v[108:111], v[32:47]
	v_cvt_pk_bf16_f32 v92, v70, v71
	v_cvt_pk_bf16_f32 v93, v68, v69
	v_cvt_pk_bf16_f32 v94, v72, v73
	v_cvt_pk_bf16_f32 v95, v74, v75
	v_add_f32_e64 v64, v64, v66
	v_add_f32_e64 v65, v65, v67
	s_waitcnt lgkmcnt(0)
	s_barrier
	v_add_f32_e32 v64, v64, v65
	v_add_f32_e32 v150, v150, v64
	s_cbranch_scc1 .LBB0_898
	v_ashrrev_i32_e32 v64, 1, v129
	v_and_or_b32 v132, v64, s88, v148
	v_mov_b64_e32 v[64:65], s[12:13]
	v_mad_i64_i32 v[64:65], s[2:3], v132, s33, v[64:65]
	v_lshlrev_b32_e32 v176, 4, v138
	s_waitcnt vmcnt(1)
	ds_write_b128 v142, v[112:115] offset:16384
	s_waitcnt vmcnt(0)
	ds_write_b128 v142, v[116:119] offset:24576
	v_lshl_add_u64 v[64:65], v[64:65], 0, v[176:177]
	global_load_dwordx4 v[124:127], v[64:65], off offset:2560
	global_load_dwordx4 v[120:123], v[64:65], off offset:2592
	global_load_dwordx4 v[116:119], v[64:65], off offset:2624
	global_load_dwordx4 v[112:115], v[64:65], off offset:2656
	v_mov_b64_e32 v[64:65], s[14:15]
	v_mad_i64_i32 v[64:65], s[2:3], v132, s33, v[64:65]
	v_and_b32_e32 v66, 16, v131
	v_mov_b32_e32 v67, v177
	v_lshl_add_u64 v[64:65], v[64:65], 0, v[66:67]
	global_load_dwordx4 v[96:99], v[64:65], off offset:1024
	global_load_dwordx4 v[100:103], v[64:65], off offset:1056
	global_load_dwordx4 v[104:107], v[64:65], off offset:1088
	global_load_dwordx4 v[108:111], v[64:65], off offset:1120
	v_lshl_add_u64 v[64:65], s[34:35], 0, v[134:135]
	v_lshlrev_b32_e32 v76, 1, v130
	v_mov_b32_e32 v77, v177
	v_lshl_add_u64 v[72:73], v[64:65], 0, v[76:77]
	s_mov_b32 s2, 0x48000
	v_add_co_u32_e32 v68, vcc, s2, v72
	s_mov_b32 s2, 0x90000
	s_nop 0
	v_addc_co_u32_e32 v69, vcc, 0, v73, vcc
	global_load_dwordx4 v[64:67], v[72:73], off offset:2048
	v_ashrrev_i32_e32 v133, 31, v132
	global_load_dwordx4 v[68:71], v[68:69], off offset:2048
	v_add_co_u32_e32 v72, vcc, s2, v72
	v_mad_i64_i32 v[78:79], s[2:3], s8, v128, 0
	v_lshl_add_u64 v[78:79], v[78:79], 1, s[10:11]
	v_addc_co_u32_e32 v73, vcc, 0, v73, vcc
	v_lshl_add_u64 v[76:77], v[78:79], 0, v[76:77]
	global_load_dwordx4 v[72:75], v[72:73], off offset:2048
	s_nop 0
	global_load_dwordx4 v[76:79], v[76:77], off
	ds_read_b128 v[128:131], v144 offset:8192
	ds_read_b128 v[134:137], v144 offset:12288
	ds_read_b128 v[146:149], v141 offset:8192
	ds_read_b128 v[152:155], v141 offset:12288
	v_exp_f32_e32 v138, v48
	v_exp_f32_e32 v142, v49
	s_waitcnt lgkmcnt(3)
	v_mfma_f32_32x32x16_bf16 v[16:31], v[128:131], v[80:83], v[16:31]
	v_exp_f32_e32 v151, v50
	v_add_f32_e32 v143, 0, v138
	v_add_f32_e32 v145, 0, v142
	v_exp_f32_e32 v156, v51
	ds_read_b128 v[48:51], v140 offset:8192
	ds_read_b128 v[128:131], v140 offset:12288
	v_exp_f32_e32 v52, v52
	s_waitcnt lgkmcnt(4)
	v_mfma_f32_32x32x16_bf16 v[0:15], v[134:137], v[80:83], v[0:15]
	v_exp_f32_e32 v53, v53
	v_exp_f32_e32 v54, v54
	v_exp_f32_e32 v55, v55
	v_add_f32_e32 v157, 0, v151
	v_add_f32_e32 v158, 0, v156
	v_add_f32_e32 v143, v52, v143
	s_waitcnt lgkmcnt(3)
	v_mfma_f32_32x32x16_bf16 v[16:31], v[146:149], v[84:87], v[16:31]
	v_add_f32_e32 v145, v53, v145
	v_add_f32_e32 v146, v54, v157
	ds_read_b128 v[80:83], v139 offset:8192
	ds_read_b128 v[134:137], v139 offset:12288
	v_exp_f32_e32 v56, v56
	v_exp_f32_e32 v57, v57
	v_exp_f32_e32 v58, v58
	s_waitcnt lgkmcnt(4)
	v_mfma_f32_32x32x16_bf16 v[0:15], v[152:155], v[84:87], v[0:15]
	v_add_f32_e32 v84, v55, v158
	v_exp_f32_e32 v59, v59
	v_exp_f32_e32 v60, v60
	v_exp_f32_e32 v32, v32
	v_exp_f32_e32 v33, v33
	v_exp_f32_e32 v34, v34
	s_waitcnt lgkmcnt(3)
	v_mfma_f32_32x32x16_bf16 v[16:31], v[48:51], v[88:91], v[16:31]
	v_cvt_pk_bf16_f32 v51, v54, v55
	v_exp_f32_e32 v54, v61
	v_exp_f32_e32 v55, v62
	v_exp_f32_e32 v61, v63
	v_exp_f32_e32 v35, v35
	v_add_f32_e32 v85, v56, v143
	v_add_f32_e32 v86, v57, v145
	v_add_f32_e32 v87, v58, v146
	v_add_f32_e32 v84, v59, v84
	v_cvt_pk_bf16_f32 v48, v138, v142
	v_cvt_pk_bf16_f32 v49, v151, v156
	v_cvt_pk_bf16_f32 v50, v52, v53
	v_add_f32_e32 v52, v60, v85
	v_add_f32_e32 v53, v54, v86
	v_add_f32_e32 v62, v55, v87
	v_add_f32_e32 v63, v61, v84
	v_exp_f32_e32 v36, v36
	v_exp_f32_e32 v37, v37
	v_exp_f32_e32 v38, v38
	v_exp_f32_e32 v39, v39
	s_waitcnt lgkmcnt(1)
	v_mfma_f32_32x32x16_bf16 v[16:31], v[80:83], v[92:95], v[16:31]
	v_add_f32_e32 v80, v32, v52
	v_add_f32_e32 v81, v33, v53
	v_cvt_pk_bf16_f32 v52, v56, v57
	v_cvt_pk_bf16_f32 v53, v58, v59
	v_cvt_pk_bf16_f32 v54, v60, v54
	v_cvt_pk_bf16_f32 v55, v55, v61
	v_add_f32_e32 v56, v34, v62
	v_add_f32_e32 v57, v35, v63
	v_exp_f32_e32 v40, v40
	v_add_f32_e32 v58, v36, v80
	v_add_f32_e32 v59, v37, v81
	v_add_f32_e32 v56, v38, v56
	v_exp_f32_e32 v41, v41
	v_add_f32_e32 v57, v39, v57
	v_mfma_f32_32x32x16_bf16 v[0:15], v[128:131], v[88:91], v[0:15]
	v_cvt_pk_bf16_f32 v32, v32, v33
	v_cvt_pk_bf16_f32 v33, v34, v35
	v_cvt_pk_bf16_f32 v34, v36, v37
	v_exp_f32_e32 v37, v42
	v_cvt_pk_bf16_f32 v35, v38, v39
	v_exp_f32_e32 v38, v43
	v_exp_f32_e32 v39, v44
	v_exp_f32_e32 v43, v45
	v_exp_f32_e32 v44, v46
	v_exp_f32_e32 v45, v47
	v_add_f32_e32 v58, v40, v58
	v_add_f32_e32 v59, v41, v59
	v_add_f32_e32 v36, v37, v56
	v_add_f32_e32 v42, v38, v57
	v_add_f32_e32 v56, v39, v58
	v_add_f32_e32 v58, v43, v59
	s_waitcnt lgkmcnt(0)
	v_mfma_f32_32x32x16_bf16 v[0:15], v[134:137], v[92:95], v[0:15]
	v_add_f32_e32 v57, v44, v36
	v_add_f32_e32 v59, v45, v42
	v_cvt_pk_bf16_f32 v36, v40, v41
	v_cvt_pk_bf16_f32 v37, v37, v38
	v_cvt_pk_bf16_f32 v38, v39, v43
	v_cvt_pk_bf16_f32 v39, v44, v45
	s_waitcnt lgkmcnt(0)
	s_barrier
	ds_read_b128 v[40:43], v144 offset:24576
	ds_read_b128 v[44:47], v144 offset:28672
	s_waitcnt lgkmcnt(1)
	v_mfma_f32_32x32x16_bf16 v[16:31], v[40:43], v[48:51], v[16:31]
	s_waitcnt lgkmcnt(0)
	v_mfma_f32_32x32x16_bf16 v[0:15], v[44:47], v[48:51], v[0:15]
	ds_read_b128 v[40:43], v141 offset:24576
	ds_read_b128 v[44:47], v141 offset:28672
	s_waitcnt lgkmcnt(1)
	v_mfma_f32_32x32x16_bf16 v[16:31], v[40:43], v[52:55], v[16:31]
	s_waitcnt lgkmcnt(0)
	v_mfma_f32_32x32x16_bf16 v[0:15], v[44:47], v[52:55], v[0:15]
	ds_read_b128 v[40:43], v140 offset:24576
	ds_read_b128 v[44:47], v140 offset:28672
	s_waitcnt lgkmcnt(1)
	v_mfma_f32_32x32x16_bf16 v[16:31], v[40:43], v[32:35], v[16:31]
	s_waitcnt lgkmcnt(0)
	v_mfma_f32_32x32x16_bf16 v[0:15], v[44:47], v[32:35], v[0:15]
	ds_read_b128 v[32:35], v139 offset:24576
	ds_read_b128 v[40:43], v139 offset:28672
	s_waitcnt lgkmcnt(1)
	v_mfma_f32_32x32x16_bf16 v[16:31], v[32:35], v[36:39], v[16:31]
	v_add_f32_e64 v32, v56, v58
	v_add_f32_e64 v33, v57, v59
	v_add_f32_e32 v32, v32, v33
	v_add_f32_e32 v32, v150, v32
	v_mov_b32_e32 v33, v32
	s_nop 1
	v_permlane32_swap_b32_e32 v32, v33
	v_add_f32_e32 v32, v32, v33
	v_div_scale_f32 v33, s[2:3], v32, v32, 1.0
	v_rcp_f32_e32 v34, v33
	s_waitcnt lgkmcnt(0)
	v_mfma_f32_32x32x16_bf16 v[0:15], v[40:43], v[36:39], v[0:15]
	s_waitcnt vmcnt(11)
	v_mov_b32_e32 v40, v127
	s_nop 1
	v_permlane32_swap_b32_e32 v125, v40
	v_fma_f32 v35, -v33, v34, 1.0
	v_fmac_f32_e32 v34, v35, v34
	v_div_scale_f32 v35, vcc, 1.0, v32, 1.0
	v_mul_f32_e32 v36, v35, v34
	v_fma_f32 v37, -v33, v36, v35
	v_fmac_f32_e32 v36, v37, v34
	v_fma_f32 v33, -v33, v36, v35
	v_div_fmas_f32 v33, v33, v34, v36
	v_mov_b32_e32 v35, v126
	v_div_fixup_f32 v34, v33, v32, 1.0
	s_nop 0
	v_permlane32_swap_b32_e32 v124, v35
	v_lshlrev_b32_e32 v38, 16, v124
	v_and_b32_e32 v39, 0xffff0000, v124
	v_mul_f32_e32 v16, v16, v34
	v_mul_f32_e32 v17, v17, v34
	v_mul_f32_e32 v18, v18, v34
	v_mul_f32_e32 v19, v19, v34
	v_mul_f32_e32 v16, v16, v38
	v_mul_f32_e32 v17, v17, v39
	v_lshlrev_b32_e32 v38, 16, v125
	v_and_b32_e32 v39, 0xffff0000, v125
	v_mul_f32_e32 v18, v18, v38
	v_mul_f32_e32 v19, v19, v39
	v_cvt_pk_bf16_f32 v16, v16, v17
	v_cvt_pk_bf16_f32 v17, v18, v19
	v_lshlrev_b32_e32 v18, 16, v35
	v_and_b32_e32 v19, 0xffff0000, v35
	v_mul_f32_e32 v20, v20, v34
	v_mul_f32_e32 v21, v21, v34
	v_mul_f32_e32 v22, v22, v34
	v_mul_f32_e32 v23, v23, v34
	v_mul_f32_e32 v18, v20, v18
	v_mul_f32_e32 v19, v21, v19
	v_lshlrev_b32_e32 v20, 16, v40
	v_and_b32_e32 v21, 0xffff0000, v40
	v_lshlrev_b64 v[32:33], 11, v[132:133]
	v_mul_f32_e32 v20, v22, v20
	v_mul_f32_e32 v21, v23, v21
	v_lshl_add_u64 v[32:33], s[6:7], 0, v[32:33]
	v_cvt_pk_bf16_f32 v18, v18, v19
	v_cvt_pk_bf16_f32 v19, v20, v21
	s_waitcnt vmcnt(10)
	v_mov_b32_e32 v22, v122
	v_lshl_add_u64 v[36:37], v[32:33], 0, v[176:177]
	v_permlane32_swap_b32_e32 v16, v18
	v_permlane32_swap_b32_e32 v17, v19
	v_permlane32_swap_b32_e32 v120, v22
	v_mov_b32_e32 v23, v123
	global_store_dwordx4 v[36:37], v[16:19], off offset:512
	s_nop 0
	v_permlane32_swap_b32_e32 v121, v23
	v_lshlrev_b32_e32 v16, 16, v120
	v_and_b32_e32 v17, 0xffff0000, v120
	v_mul_f32_e32 v18, v24, v34
	v_mul_f32_e32 v19, v25, v34
	v_mul_f32_e32 v20, v26, v34
	v_mul_f32_e32 v21, v27, v34
	v_mul_f32_e32 v16, v18, v16
	v_mul_f32_e32 v17, v19, v17
	v_lshlrev_b32_e32 v18, 16, v121
	v_and_b32_e32 v19, 0xffff0000, v121
	v_mul_f32_e32 v18, v20, v18
	v_mul_f32_e32 v19, v21, v19
	v_cvt_pk_bf16_f32 v16, v16, v17
	v_cvt_pk_bf16_f32 v17, v18, v19
	v_lshlrev_b32_e32 v18, 16, v22
	v_and_b32_e32 v19, 0xffff0000, v22
	v_mul_f32_e32 v20, v28, v34
	v_mul_f32_e32 v21, v29, v34
	v_mul_f32_e32 v0, v0, v34
	v_mul_f32_e32 v1, v1, v34
	v_mul_f32_e32 v18, v20, v18
	v_mul_f32_e32 v19, v21, v19
	v_lshlrev_b32_e32 v20, 16, v23
	v_and_b32_e32 v21, 0xffff0000, v23
	v_mul_f32_e32 v22, v30, v34
	v_mul_f32_e32 v23, v31, v34
	v_cvt_pk_bf16_f32 v18, v18, v19
	v_mul_f32_e32 v20, v22, v20
	v_mul_f32_e32 v21, v23, v21
	s_nop 0
	v_permlane32_swap_b32_e32 v16, v18
	v_cvt_pk_bf16_f32 v19, v20, v21
	s_nop 1
	v_permlane32_swap_b32_e32 v17, v19
	global_store_dwordx4 v[36:37], v[16:19], off offset:544
	v_mul_f32_e32 v2, v2, v34
	v_mul_f32_e32 v3, v3, v34
	v_mul_f32_e32 v4, v4, v34
	v_mul_f32_e32 v5, v5, v34
	s_waitcnt vmcnt(11)
	v_mov_b32_e32 v18, v118
	s_nop 1
	v_permlane32_swap_b32_e32 v116, v18
	v_mov_b32_e32 v19, v119
	s_nop 1
	v_permlane32_swap_b32_e32 v117, v19
	v_lshlrev_b32_e32 v16, 16, v116
	v_and_b32_e32 v17, 0xffff0000, v116
	v_mul_f32_e32 v0, v0, v16
	v_mul_f32_e32 v1, v1, v17
	v_lshlrev_b32_e32 v16, 16, v117
	v_and_b32_e32 v17, 0xffff0000, v117
	v_mul_f32_e32 v2, v2, v16
	v_mul_f32_e32 v3, v3, v17
	v_cvt_pk_bf16_f32 v0, v0, v1
	v_cvt_pk_bf16_f32 v1, v2, v3
	v_lshlrev_b32_e32 v2, 16, v18
	v_and_b32_e32 v3, 0xffff0000, v18
	v_mul_f32_e32 v2, v4, v2
	v_mul_f32_e32 v3, v5, v3
	v_lshlrev_b32_e32 v4, 16, v19
	v_and_b32_e32 v5, 0xffff0000, v19
	v_mul_f32_e32 v6, v6, v34
	v_mul_f32_e32 v7, v7, v34
	v_cvt_pk_bf16_f32 v2, v2, v3
	v_mul_f32_e32 v4, v6, v4
	v_mul_f32_e32 v5, v7, v5
	s_waitcnt vmcnt(10)
	v_mov_b32_e32 v6, v114
	v_cvt_pk_bf16_f32 v3, v4, v5
	v_permlane32_swap_b32_e32 v0, v2
	s_nop 0
	v_permlane32_swap_b32_e32 v1, v3
	v_permlane32_swap_b32_e32 v112, v6
	v_mov_b32_e32 v7, v115
	global_store_dwordx4 v[36:37], v[0:3], off offset:576
	s_nop 0
	v_permlane32_swap_b32_e32 v113, v7
	v_lshlrev_b32_e32 v0, 16, v112
	v_and_b32_e32 v1, 0xffff0000, v112
	v_mul_f32_e32 v2, v8, v34
	v_mul_f32_e32 v3, v9, v34
	v_mul_f32_e32 v4, v10, v34
	v_mul_f32_e32 v5, v11, v34
	v_mul_f32_e32 v0, v2, v0
	v_mul_f32_e32 v1, v3, v1
	v_lshlrev_b32_e32 v2, 16, v113
	v_and_b32_e32 v3, 0xffff0000, v113
	v_mul_f32_e32 v2, v4, v2
	v_mul_f32_e32 v3, v5, v3
	v_cvt_pk_bf16_f32 v0, v0, v1
	v_cvt_pk_bf16_f32 v1, v2, v3
	v_lshlrev_b32_e32 v2, 16, v6
	v_and_b32_e32 v3, 0xffff0000, v6
	v_mul_f32_e32 v4, v12, v34
	v_mul_f32_e32 v5, v13, v34
	s_mov_b64 s[2:3], 0x200
	v_mul_f32_e32 v2, v4, v2
	v_mul_f32_e32 v3, v5, v3
	v_lshlrev_b32_e32 v4, 16, v7
	v_and_b32_e32 v5, 0xffff0000, v7
	v_mul_f32_e32 v6, v14, v34
	v_mul_f32_e32 v7, v15, v34
	v_cvt_pk_bf16_f32 v2, v2, v3
	v_mul_f32_e32 v4, v6, v4
	v_mul_f32_e32 v5, v7, v5
	v_lshl_add_u64 v[32:33], v[36:37], 0, s[2:3]
	v_cvt_pk_bf16_f32 v3, v4, v5
	v_permlane32_swap_b32_e32 v0, v2
	s_nop 0
	v_permlane32_swap_b32_e32 v1, v3
	s_branch .LBB0_876
